# gdn_chunk right-hand-side scaling loop: four rows per trip with their LDS reads issued together
# speedup vs baseline: 1.0084x; 1.0084x over previous
; DI void gdn_chunk(CP c, int l, int item, float* sm) {
;     ...
;     for (int e = tid; e < 64 * 128; e += 512) { const int i = e >> 7, cc = e & 127; const float bi = bs[i];
;         R[i * 260 + cc] *= bi; R[i * 260 + 128 + cc] = Ks[i * 132 + cc] * bi * __expf(gs[i]); }
.LBB0_946:
	v_ashrrev_i32_e32 v6, 7, v3
	v_lshl_add_u32 v8, v6, 2, 0
	v_add_u32_e32 v4, 0x25100, v8
	v_add_u32_e32 v10, 0x25000, v8
	v_mad_u32_u24 v34, v6, s26, v2
	v_mad_u32_u24 v35, v6, s14, v0
	s_lshl_b32 s27, s14, 2
	v_add_u32_e32 v36, s27, v35
	v_add_u32_e32 v37, s27, v36
	v_add_u32_e32 v42, s27, v37
	ds_read_b32 v43, v4
	ds_read_b32 v65, v34
	ds_read_b32 v44, v4 offset:16
	ds_read_b32 v66, v34 offset:4160
	ds_read_b32 v45, v4 offset:32
	ds_read_b32 v67, v34 offset:8320
	ds_read_b32 v64, v4 offset:48
	ds_read_b32 v70, v34 offset:12480
	ds_read_b32 v71, v35 offset:33792
	ds_read_b32 v75, v10
	ds_read_b32 v72, v36 offset:33792
	ds_read_b32 v76, v10 offset:16
	ds_read_b32 v73, v37 offset:33792
	ds_read_b32 v77, v10 offset:32
	ds_read_b32 v74, v42 offset:33792
	ds_read_b32 v78, v10 offset:48
	s_movk_i32 s0, 0x17ff
	v_cmp_lt_i32_e32 vcc, s0, v3
	s_or_b64 s[12:13], vcc, s[12:13]
	s_waitcnt lgkmcnt(14)
	v_mul_f32_e32 v65, v43, v65
	s_waitcnt lgkmcnt(12)
	v_mul_f32_e32 v66, v44, v66
	s_waitcnt lgkmcnt(10)
	v_mul_f32_e32 v67, v45, v67
	s_waitcnt lgkmcnt(8)
	v_mul_f32_e32 v70, v64, v70
	s_waitcnt lgkmcnt(0)
	ds_write_b32 v34, v65
	ds_write_b32 v34, v66 offset:4160
	ds_write_b32 v34, v67 offset:8320
	ds_write_b32 v34, v70 offset:12480
	v_mul_f32_e32 v71, v43, v71
	v_mul_f32_e32 v75, 0x3fb8aa3b, v75
	v_exp_f32_e32 v75, v75
	v_mul_f32_e32 v72, v44, v72
	v_mul_f32_e32 v76, 0x3fb8aa3b, v76
	v_exp_f32_e32 v76, v76
	v_mul_f32_e32 v73, v45, v73
	v_mul_f32_e32 v77, 0x3fb8aa3b, v77
	v_exp_f32_e32 v77, v77
	v_mul_f32_e32 v74, v64, v74
	v_mul_f32_e32 v78, 0x3fb8aa3b, v78
	v_exp_f32_e32 v78, v78
	s_nop 0
	v_mul_f32_e32 v71, v71, v75
	ds_write_b32 v34, v71 offset:512
	v_mul_f32_e32 v72, v72, v76
	ds_write_b32 v34, v72 offset:4672
	v_mul_f32_e32 v73, v73, v77
	ds_write_b32 v34, v73 offset:8832
	v_mul_f32_e32 v74, v74, v78
	ds_write_b32 v34, v74 offset:12992
	v_add_u32_e32 v3, 0x800, v3
	s_andn2_b64 exec, exec, s[12:13]
	s_cbranch_execnz .LBB0_946
